# V^T fragment direct reads extended to the lat-B loop (one pair type), ctx-A and ctx-B attention instantiations
# speedup vs baseline: 1.0111x; 1.0052x over previous
.LBB0_203:
	v_sub_f32_e32 v4, v96, v1
	v_exp_f32_e32 v9, v4
	v_sub_f32_e32 v5, v97, v1
	v_exp_f32_e32 v10, v5
	v_sub_f32_e32 v5, v98, v1
	v_exp_f32_e32 v11, v5
	v_sub_f32_e32 v5, v99, v1
	v_exp_f32_e32 v13, v5
	v_sub_f32_e32 v5, v100, v1
	v_add_f32_e32 v4, 0, v9
	v_exp_f32_e32 v14, v5
	v_sub_f32_e32 v5, v101, v1
	v_add_f32_e32 v4, v10, v4
	v_exp_f32_e32 v15, v5
	v_sub_f32_e32 v5, v102, v1
	v_add_f32_e32 v4, v11, v4
	v_exp_f32_e32 v96, v5
	v_sub_f32_e32 v5, v103, v1
	v_add_f32_e32 v4, v13, v4
	v_exp_f32_e32 v97, v5
	v_sub_f32_e32 v5, v104, v1
	v_add_f32_e32 v4, v14, v4
	v_exp_f32_e32 v5, v5
	v_sub_f32_e32 v6, v105, v1
	v_add_f32_e32 v4, v15, v4
	v_exp_f32_e32 v6, v6
	v_sub_f32_e32 v7, v106, v1
	v_add_f32_e32 v4, v96, v4
	v_exp_f32_e32 v7, v7
	v_sub_f32_e32 v12, v107, v1
	v_add_f32_e32 v4, v97, v4
	v_exp_f32_e32 v12, v12
	v_sub_f32_e32 v98, v108, v1
	v_add_f32_e32 v4, v5, v4
	v_exp_f32_e32 v98, v98
	v_sub_f32_e32 v99, v109, v1
	v_add_f32_e32 v4, v6, v4
	v_exp_f32_e32 v99, v99
	v_sub_f32_e32 v100, v110, v1
	v_add_f32_e32 v4, v7, v4
	v_exp_f32_e32 v100, v100
	v_sub_f32_e32 v101, v111, v1
	v_add_f32_e32 v4, v12, v4
	v_exp_f32_e32 v101, v101
	v_add_f32_e32 v4, v98, v4
	v_add_f32_e32 v4, v99, v4
	v_add_f32_e32 v4, v100, v4
	v_add_f32_e32 v4, v101, v4
	v_add_f32_e32 v3, v3, v4
	v_cvt_pk_bf16_f32 v4, v5, v6
	v_cvt_pk_bf16_f32 v5, v7, v12
	v_cvt_pk_bf16_f32 v12, v9, v10
	v_sub_f32_e32 v9, v80, v205
	v_cvt_pk_bf16_f32 v13, v11, v13
	v_exp_f32_e32 v9, v9
	v_sub_f32_e32 v11, v81, v205
	v_exp_f32_e32 v11, v11
	v_sub_f32_e32 v80, v82, v205
	v_exp_f32_e32 v81, v80
	v_sub_f32_e32 v80, v83, v205
	v_exp_f32_e32 v82, v80
	v_sub_f32_e32 v80, v84, v205
	v_add_f32_e32 v10, 0, v9
	v_exp_f32_e32 v83, v80
	v_sub_f32_e32 v80, v85, v205
	v_add_f32_e32 v10, v11, v10
	v_exp_f32_e32 v84, v80
	v_sub_f32_e32 v80, v86, v205
	v_add_f32_e32 v10, v81, v10
	v_exp_f32_e32 v85, v80
	v_sub_f32_e32 v80, v87, v205
	v_add_f32_e32 v10, v82, v10
	v_exp_f32_e32 v86, v80
	v_sub_f32_e32 v80, v88, v205
	v_add_f32_e32 v10, v83, v10
	v_exp_f32_e32 v87, v80
	v_sub_f32_e32 v80, v89, v205
	v_add_f32_e32 v10, v84, v10
	v_exp_f32_e32 v88, v80
	v_sub_f32_e32 v80, v90, v205
	v_add_f32_e32 v10, v85, v10
	v_exp_f32_e32 v89, v80
	v_sub_f32_e32 v80, v91, v205
	v_add_f32_e32 v10, v86, v10
	v_exp_f32_e32 v90, v80
	v_sub_f32_e32 v80, v92, v205
	v_add_f32_e32 v10, v87, v10
	v_exp_f32_e32 v91, v80
	v_sub_f32_e32 v80, v93, v205
	v_add_f32_e32 v10, v88, v10
	v_exp_f32_e32 v92, v80
	v_sub_f32_e32 v80, v94, v205
	v_add_f32_e32 v10, v89, v10
	v_exp_f32_e32 v93, v80
	v_sub_f32_e32 v80, v95, v205
	v_add_f32_e32 v10, v90, v10
	v_exp_f32_e32 v94, v80
	v_add_f32_e32 v10, v91, v10
	v_add_f32_e32 v10, v92, v10
	v_add_f32_e32 v10, v93, v10
	v_add_f32_e32 v10, v94, v10
	v_add_f32_e32 v208, v8, v10
	v_cvt_pk_bf16_f32 v81, v81, v82
	v_cvt_pk_bf16_f32 v82, v83, v84
	v_cvt_pk_bf16_f32 v8, v87, v88
	v_lshl_add_u32 v84, v204, 1, v219
	v_lshl_add_u32 v88, v203, 1, v219
	v_cvt_pk_bf16_f32 v80, v9, v11
	v_cvt_pk_bf16_f32 v83, v85, v86
	v_cvt_pk_bf16_f32 v9, v89, v90
	v_cvt_pk_bf16_f32 v10, v91, v92
	ds_read_b64 v[238:239], v84 offset:8192
	ds_read_b64 v[242:243], v84 offset:12288
	ds_read_b64 v[240:241], v88 offset:8192
	ds_read_b64 v[244:245], v88 offset:12288
	v_cvt_pk_bf16_f32 v11, v93, v94
	v_cvt_pk_bf16_f32 v14, v14, v15
	v_cvt_pk_bf16_f32 v15, v96, v97
	s_waitcnt lgkmcnt(0)
	v_mfma_f32_32x32x16_bf16 v[64:79], v[238:241], v[12:15], v[64:79]
	v_cvt_pk_bf16_f32 v6, v98, v99
	v_cvt_pk_bf16_f32 v7, v100, v101
	s_add_i32 s45, s45, 1
	s_add_i32 s2, s38, 1
	s_cmp_lg_u32 s38, 2
	s_cselect_b32 s38, s2, 0
	s_mov_b64 s[2:3], 0x1000
	v_mfma_f32_32x32x16_bf16 v[32:47], v[238:241], v[80:83], v[32:47]
	v_lshl_add_u64 v[162:163], v[162:163], 0, s[22:23]
	v_lshl_add_u64 v[164:165], v[164:165], 0, s[2:3]
	v_lshl_add_u64 v[166:167], v[166:167], 0, s[24:25]
	s_cmp_lg_u32 s45, 3
	v_mfma_f32_32x32x16_bf16 v[48:63], v[242:245], v[12:15], v[48:63]
	v_lshl_add_u32 v12, v202, 1, v219
	ds_read2st64_b64 v[12:15], v12 offset0:16 offset1:24
	s_waitcnt lgkmcnt(0)
	v_mov_b32_e32 v84, v12
	v_mfma_f32_32x32x16_bf16 v[16:31], v[242:245], v[80:83], v[16:31]
	v_lshl_add_u32 v80, v201, 1, v219
	ds_read2st64_b64 v[80:83], v80 offset0:16 offset1:24
	v_mov_b32_e32 v85, v13
	s_waitcnt lgkmcnt(0)
	v_mov_b32_e32 v86, v80
	v_mov_b32_e32 v87, v81
	v_mov_b32_e32 v80, v14
	v_mov_b32_e32 v81, v15
	v_mfma_f32_32x32x16_bf16 v[64:79], v[84:87], v[4:7], v[64:79]
	v_mfma_f32_32x32x16_bf16 v[32:47], v[84:87], v[8:11], v[32:47]
	v_mfma_f32_32x32x16_bf16 v[48:63], v[80:83], v[4:7], v[48:63]
	v_mfma_f32_32x32x16_bf16 v[16:31], v[80:83], v[8:11], v[16:31]
	s_cbranch_scc0 .LBB0_214

.LBB0_210:
	v_sub_f32_e32 v4, v96, v1
	v_exp_f32_e32 v4, v4
	v_sub_f32_e32 v6, v97, v1
	v_exp_f32_e32 v6, v6
	v_sub_f32_e32 v7, v98, v1
	v_exp_f32_e32 v7, v7
	v_sub_f32_e32 v8, v99, v1
	v_exp_f32_e32 v8, v8
	v_add_f32_e32 v5, 0, v4
	v_add_f32_e32 v5, v6, v5
	v_add_f32_e32 v5, v7, v5
	v_add_f32_e32 v5, v8, v5
	v_cvt_pk_bf16_f32 v97, v7, v8
	v_sub_f32_e32 v8, v80, v205
	v_exp_f32_e32 v224, v8
	v_sub_f32_e32 v8, v81, v205
	v_exp_f32_e32 v226, v8
	v_sub_f32_e32 v8, v82, v205
	v_exp_f32_e32 v227, v8
	v_sub_f32_e32 v8, v83, v205
	v_exp_f32_e32 v228, v8
	v_sub_f32_e32 v8, v84, v205
	v_exp_f32_e32 v229, v8
	v_sub_f32_e32 v8, v85, v205
	v_exp_f32_e32 v230, v8
	v_sub_f32_e32 v8, v86, v205
	v_exp_f32_e32 v231, v8
	v_sub_f32_e32 v8, v87, v205
	v_exp_f32_e32 v232, v8
	v_sub_f32_e32 v8, v88, v205
	v_exp_f32_e32 v233, v8
	v_sub_f32_e32 v8, v89, v205
	v_add3_u32 v219, v219, v209, v160
	v_exp_f32_e32 v234, v8
	v_sub_f32_e32 v8, v90, v205
	v_lshl_add_u32 v84, v211, 1, v219
	v_lshl_add_u32 v88, v210, 1, v219
	v_exp_f32_e32 v235, v8
	v_sub_f32_e32 v8, v91, v205
	ds_read_b64 v[238:239], v84 offset:8192
	ds_read_b64 v[242:243], v84 offset:12288
	ds_read_b64 v[240:241], v88 offset:8192
	ds_read_b64 v[244:245], v88 offset:12288
	v_exp_f32_e32 v236, v8
	v_sub_f32_e32 v8, v92, v205
	v_sub_f32_e32 v9, v100, v1
	v_sub_f32_e32 v96, v103, v1
	v_exp_f32_e32 v237, v8
	v_sub_f32_e32 v8, v93, v205
	v_exp_f32_e32 v9, v9
	v_sub_f32_e32 v10, v101, v1
	v_exp_f32_e32 v99, v96
	v_sub_f32_e32 v96, v104, v1
	v_exp_f32_e32 v222, v8
	v_sub_f32_e32 v8, v94, v205
	v_exp_f32_e32 v10, v10
	v_sub_f32_e32 v11, v102, v1
	v_exp_f32_e32 v100, v96
	v_sub_f32_e32 v96, v105, v1
	v_exp_f32_e32 v223, v8
	v_sub_f32_e32 v8, v95, v205
	s_waitcnt lgkmcnt(0)
	v_exp_f32_e32 v11, v11
	v_exp_f32_e32 v101, v96
	v_sub_f32_e32 v96, v106, v1
	v_exp_f32_e32 v102, v96
	v_sub_f32_e32 v96, v107, v1
	v_add_f32_e32 v5, v9, v5
	v_exp_f32_e32 v103, v96
	v_sub_f32_e32 v96, v108, v1
	v_add_f32_e32 v5, v10, v5
	v_exp_f32_e32 v104, v96
	v_sub_f32_e32 v96, v109, v1
	v_cvt_pk_bf16_f32 v80, v224, v226
	v_cvt_pk_bf16_f32 v81, v227, v228
	v_cvt_pk_bf16_f32 v82, v229, v230
	v_cvt_pk_bf16_f32 v83, v231, v232
	v_add_f32_e32 v5, v11, v5
	v_exp_f32_e32 v105, v96
	v_sub_f32_e32 v96, v110, v1
	v_mfma_f32_32x32x16_bf16 v[32:47], v[238:241], v[80:83], v[32:47]
	v_lshl_add_u32 v84, v206, 1, v219
	v_add_f32_e32 v5, v99, v5
	v_exp_f32_e32 v106, v96
	v_sub_f32_e32 v96, v111, v1
	ds_read2st64_b64 v[84:87], v84 offset0:16 offset1:24
	v_add_f32_e32 v5, v100, v5
	v_exp_f32_e32 v107, v96
	v_mfma_f32_32x32x16_bf16 v[16:31], v[242:245], v[80:83], v[16:31]
	v_lshl_add_u32 v80, v207, 1, v219
	ds_read2st64_b64 v[80:83], v80 offset0:16 offset1:24
	v_cvt_pk_bf16_f32 v96, v4, v6
	v_cvt_pk_bf16_f32 v98, v9, v10
	v_cvt_pk_bf16_f32 v99, v11, v99
	v_add_f32_e32 v5, v101, v5
	v_add_f32_e32 v5, v102, v5
	v_mfma_f32_32x32x16_bf16 v[64:79], v[238:241], v[96:99], v[64:79]
	v_add_f32_e32 v5, v103, v5
	v_add_f32_e32 v5, v104, v5
	v_add_f32_e32 v5, v105, v5
	v_add_f32_e32 v5, v106, v5
	v_add_f32_e32 v5, v107, v5
	v_add_f32_e32 v3, v3, v5
	v_cvt_pk_bf16_f32 v4, v100, v101
	v_mfma_f32_32x32x16_bf16 v[48:63], v[242:245], v[96:99], v[48:63]
	s_waitcnt lgkmcnt(0)
	v_mov_b32_e32 v88, v80
	v_mov_b32_e32 v89, v81
	v_mov_b32_e32 v90, v84
	v_mov_b32_e32 v91, v85
	v_mov_b32_e32 v84, v82
	v_mov_b32_e32 v85, v83
	v_cvt_pk_bf16_f32 v5, v102, v103
	v_cvt_pk_bf16_f32 v6, v104, v105
	v_cvt_pk_bf16_f32 v7, v106, v107
	v_exp_f32_e32 v225, v8
	v_cvt_pk_bf16_f32 v8, v233, v234
	v_mfma_f32_32x32x16_bf16 v[64:79], v[88:91], v[4:7], v[64:79]
	v_cvt_pk_bf16_f32 v9, v235, v236
	v_cvt_pk_bf16_f32 v10, v237, v222
	v_cvt_pk_bf16_f32 v11, v223, v225
	v_mfma_f32_32x32x16_bf16 v[48:63], v[84:87], v[4:7], v[48:63]
	ds_read_b128 v[4:7], v220 offset:4096
	v_mfma_f32_32x32x16_bf16 v[32:47], v[88:91], v[8:11], v[32:47]
	v_mfma_f32_32x32x16_bf16 v[16:31], v[84:87], v[8:11], v[16:31]
	s_waitcnt lgkmcnt(0)
	v_mfma_f32_32x32x16_bf16 v[96:111], v[4:7], v[152:155], 0
	v_mfma_f32_32x32x16_bf16 v[80:95], v[4:7], v[156:159], 0
	ds_read_b128 v[4:7], v14 offset:4096
	s_waitcnt lgkmcnt(0)
	v_mfma_f32_32x32x16_bf16 v[96:111], v[4:7], v[140:143], v[96:111]
	v_mfma_f32_32x32x16_bf16 v[80:95], v[4:7], v[148:151], v[80:95]
	ds_read_b128 v[4:7], v221 offset:4096
	s_waitcnt lgkmcnt(0)
	v_mfma_f32_32x32x16_bf16 v[96:111], v[4:7], v[136:139], v[96:111]
	v_mfma_f32_32x32x16_bf16 v[80:95], v[4:7], v[144:147], v[80:95]
	ds_read_b128 v[4:7], v13 offset:4096
	s_waitcnt lgkmcnt(0)
	v_mfma_f32_32x32x16_bf16 v[96:111], v[4:7], v[124:127], v[96:111]
	v_mfma_f32_32x32x16_bf16 v[80:95], v[4:7], v[132:135], v[80:95]
	ds_read_b128 v[4:7], v15 offset:18432
	s_waitcnt lgkmcnt(0)
	v_mfma_f32_32x32x16_bf16 v[96:111], v[4:7], v[120:123], v[96:111]
	v_mfma_f32_32x32x16_bf16 v[80:95], v[4:7], v[128:131], v[80:95]
	ds_read_b128 v[4:7], v12 offset:18432
	s_waitcnt lgkmcnt(0)
	v_mfma_f32_32x32x16_bf16 v[96:111], v[4:7], v[112:115], v[96:111]
	v_mfma_f32_32x32x16_bf16 v[80:95], v[4:7], v[116:119], v[80:95]
	s_nop 10
	v_max_f32_e32 v4, v97, v97
	v_max_f32_e32 v5, v96, v96
	v_max_f32_e32 v4, v5, v4
	v_max3_f32 v4, v4, v98, v99
	v_max3_f32 v4, v4, v100, v101
	v_max3_f32 v4, v4, v102, v103
	v_max3_f32 v4, v4, v104, v105
	v_max3_f32 v4, v4, v106, v107
	v_max3_f32 v4, v4, v108, v109
	v_max3_f32 v4, v4, v110, v111
	ds_bpermute_b32 v5, v0, v4
	s_waitcnt lgkmcnt(0)
	v_max_f32_e32 v5, v5, v5
	v_max_f32_e32 v4, v4, v5
	v_add_f32_e32 v5, 0x41000000, v1
	v_cmp_gt_f32_e32 vcc, v4, v5
	s_cbranch_vccz .LBB0_212
	v_max_f32_e32 v4, v4, v4
	v_max_f32_e32 v5, v1, v1
	v_max_f32_e32 v5, v5, v4
	v_sub_f32_e32 v1, v1, v5
	v_exp_f32_e32 v4, v1
	v_mov_b32_e32 v1, v5
	v_mul_f32_e32 v3, v3, v4
	v_pk_mul_f32 v[78:79], v[78:79], v[4:5] op_sel_hi:[1,0]
	v_pk_mul_f32 v[76:77], v[76:77], v[4:5] op_sel_hi:[1,0]
	v_pk_mul_f32 v[74:75], v[74:75], v[4:5] op_sel_hi:[1,0]
	v_pk_mul_f32 v[72:73], v[72:73], v[4:5] op_sel_hi:[1,0]
	v_pk_mul_f32 v[70:71], v[70:71], v[4:5] op_sel_hi:[1,0]
	v_pk_mul_f32 v[68:69], v[68:69], v[4:5] op_sel_hi:[1,0]
	v_pk_mul_f32 v[66:67], v[66:67], v[4:5] op_sel_hi:[1,0]
	v_pk_mul_f32 v[64:65], v[64:65], v[4:5] op_sel_hi:[1,0]
	v_pk_mul_f32 v[62:63], v[62:63], v[4:5] op_sel_hi:[1,0]
	v_pk_mul_f32 v[60:61], v[60:61], v[4:5] op_sel_hi:[1,0]
	v_pk_mul_f32 v[58:59], v[58:59], v[4:5] op_sel_hi:[1,0]
	v_pk_mul_f32 v[56:57], v[56:57], v[4:5] op_sel_hi:[1,0]
	v_pk_mul_f32 v[54:55], v[54:55], v[4:5] op_sel_hi:[1,0]
	v_pk_mul_f32 v[52:53], v[52:53], v[4:5] op_sel_hi:[1,0]
	v_pk_mul_f32 v[50:51], v[50:51], v[4:5] op_sel_hi:[1,0]
	v_pk_mul_f32 v[48:49], v[48:49], v[4:5] op_sel_hi:[1,0]

.LBB0_218:
	v_sub_f32_e32 v4, v96, v1
	v_exp_f32_e32 v4, v4
	v_sub_f32_e32 v6, v97, v1
	v_exp_f32_e32 v6, v6
	v_sub_f32_e32 v7, v98, v1
	v_exp_f32_e32 v7, v7
	v_sub_f32_e32 v8, v99, v1
	v_exp_f32_e32 v8, v8
	v_sub_f32_e32 v9, v100, v1
	v_add_f32_e32 v5, 0, v4
	v_exp_f32_e32 v9, v9
	v_sub_f32_e32 v10, v101, v1
	v_add_f32_e32 v5, v6, v5
	v_exp_f32_e32 v10, v10
	v_sub_f32_e32 v11, v102, v1
	v_add_f32_e32 v5, v7, v5
	v_exp_f32_e32 v11, v11
	v_sub_f32_e32 v12, v103, v1
	v_add_f32_e32 v5, v8, v5
	v_exp_f32_e32 v99, v12
	v_sub_f32_e32 v12, v104, v1
	v_add_f32_e32 v5, v9, v5
	v_exp_f32_e32 v100, v12
	v_sub_f32_e32 v12, v105, v1
	v_add_f32_e32 v5, v10, v5
	v_exp_f32_e32 v101, v12
	v_sub_f32_e32 v12, v106, v1
	v_add_f32_e32 v5, v11, v5
	v_exp_f32_e32 v102, v12
	v_sub_f32_e32 v12, v107, v1
	v_add_f32_e32 v5, v99, v5
	v_exp_f32_e32 v103, v12
	v_sub_f32_e32 v12, v108, v1
	v_add_f32_e32 v5, v100, v5
	v_exp_f32_e32 v104, v12
	v_sub_f32_e32 v12, v109, v1
	v_add_f32_e32 v5, v101, v5
	v_exp_f32_e32 v105, v12
	v_sub_f32_e32 v12, v110, v1
	v_add_f32_e32 v5, v102, v5
	v_exp_f32_e32 v106, v12
	v_sub_f32_e32 v12, v111, v1
	v_add_f32_e32 v5, v103, v5
	v_exp_f32_e32 v107, v12
	v_add_f32_e32 v5, v104, v5
	v_add_f32_e32 v5, v105, v5
	v_add_f32_e32 v5, v106, v5
	v_add_f32_e32 v5, v107, v5
	v_add_f32_e32 v12, v3, v5
	v_sub_f32_e32 v3, v80, v205
	v_exp_f32_e32 v167, v3
	v_sub_f32_e32 v3, v81, v205
	v_exp_f32_e32 v213, v3
	v_sub_f32_e32 v3, v82, v205
	v_exp_f32_e32 v214, v3
	v_sub_f32_e32 v3, v83, v205
	v_exp_f32_e32 v216, v3
	v_sub_f32_e32 v3, v84, v205
	v_exp_f32_e32 v217, v3
	v_sub_f32_e32 v3, v85, v205
	v_exp_f32_e32 v218, v3
	v_sub_f32_e32 v3, v86, v205
	v_exp_f32_e32 v219, v3
	v_sub_f32_e32 v3, v87, v205
	v_exp_f32_e32 v220, v3
	v_sub_f32_e32 v3, v88, v205
	v_exp_f32_e32 v221, v3
	v_sub_f32_e32 v3, v89, v205
	v_exp_f32_e32 v222, v3
	v_sub_f32_e32 v3, v90, v205
	v_exp_f32_e32 v223, v3
	v_sub_f32_e32 v3, v91, v205
	v_exp_f32_e32 v224, v3
	v_sub_f32_e32 v3, v92, v205
	v_exp_f32_e32 v225, v3
	v_sub_f32_e32 v3, v93, v205
	v_exp_f32_e32 v165, v3
	v_sub_f32_e32 v3, v94, v205
	v_exp_f32_e32 v166, v3
	v_sub_f32_e32 v3, v95, v205
	v_exp_f32_e32 v212, v3
	v_add3_u32 v3, v215, v209, v160
	v_lshl_add_u32 v84, v211, 1, v3
	v_lshl_add_u32 v88, v210, 1, v3
	ds_read_b64 v[238:239], v84 offset:8192
	ds_read_b64 v[242:243], v84 offset:12288
	ds_read_b64 v[240:241], v88 offset:8192
	ds_read_b64 v[244:245], v88 offset:12288
	v_cvt_pk_bf16_f32 v80, v167, v213
	v_cvt_pk_bf16_f32 v81, v214, v216
	v_cvt_pk_bf16_f32 v82, v217, v218
	s_waitcnt lgkmcnt(0)
	v_cvt_pk_bf16_f32 v83, v219, v220
	v_lshl_add_u32 v84, v206, 1, v3
	ds_read2st64_b64 v[84:87], v84 offset0:16 offset1:24
	v_mfma_f32_32x32x16_bf16 v[32:47], v[238:241], v[80:83], v[32:47]
	v_cvt_pk_bf16_f32 v96, v4, v6
	v_cvt_pk_bf16_f32 v97, v7, v8
	v_cvt_pk_bf16_f32 v98, v9, v10
	v_cvt_pk_bf16_f32 v99, v11, v99
	v_cvt_pk_bf16_f32 v4, v100, v101
	v_cvt_pk_bf16_f32 v5, v102, v103
	v_cvt_pk_bf16_f32 v6, v104, v105
	v_mfma_f32_32x32x16_bf16 v[16:31], v[242:245], v[80:83], v[16:31]
	v_lshl_add_u32 v80, v207, 1, v3
	ds_read2st64_b64 v[80:83], v80 offset0:16 offset1:24
	v_cvt_pk_bf16_f32 v7, v106, v107
	v_cvt_pk_bf16_f32 v8, v221, v222
	v_cvt_pk_bf16_f32 v9, v223, v224
	v_cvt_pk_bf16_f32 v10, v225, v165
	v_cvt_pk_bf16_f32 v11, v166, v212
	v_mfma_f32_32x32x16_bf16 v[64:79], v[238:241], v[96:99], v[64:79]
	v_mfma_f32_32x32x16_bf16 v[48:63], v[242:245], v[96:99], v[48:63]
	s_waitcnt lgkmcnt(0)
	v_mov_b32_e32 v88, v80
	v_mov_b32_e32 v89, v81
	v_mov_b32_e32 v90, v84
	v_mov_b32_e32 v91, v85
	v_mov_b32_e32 v84, v82
	v_mov_b32_e32 v85, v83
	v_mfma_f32_32x32x16_bf16 v[64:79], v[88:91], v[4:7], v[64:79]
	s_nop 0
	v_mfma_f32_32x32x16_bf16 v[48:63], v[84:87], v[4:7], v[48:63]
	ds_read_b128 v[4:7], v14 offset:4096
	v_mfma_f32_32x32x16_bf16 v[32:47], v[88:91], v[8:11], v[32:47]
	v_mfma_f32_32x32x16_bf16 v[16:31], v[84:87], v[8:11], v[16:31]
	s_waitcnt lgkmcnt(0)
	v_mfma_f32_32x32x16_bf16 v[96:111], v[4:7], v[152:155], 0
	v_mfma_f32_32x32x16_bf16 v[80:95], v[4:7], v[156:159], 0
	ds_read_b128 v[4:7], v15 offset:4096
	s_waitcnt lgkmcnt(0)
	v_mfma_f32_32x32x16_bf16 v[96:111], v[4:7], v[140:143], v[96:111]
	v_mfma_f32_32x32x16_bf16 v[80:95], v[4:7], v[148:151], v[80:95]
	ds_read_b128 v[4:7], v162 offset:4096
	s_waitcnt lgkmcnt(0)
	v_mfma_f32_32x32x16_bf16 v[96:111], v[4:7], v[136:139], v[96:111]
	v_mfma_f32_32x32x16_bf16 v[80:95], v[4:7], v[144:147], v[80:95]
	ds_read_b128 v[4:7], v163 offset:4096
	s_waitcnt lgkmcnt(0)
	v_mfma_f32_32x32x16_bf16 v[96:111], v[4:7], v[124:127], v[96:111]
	v_mfma_f32_32x32x16_bf16 v[80:95], v[4:7], v[132:135], v[80:95]
	ds_read_b128 v[4:7], v164 offset:18432
	s_waitcnt lgkmcnt(0)
	v_mfma_f32_32x32x16_bf16 v[96:111], v[4:7], v[120:123], v[96:111]
	v_mfma_f32_32x32x16_bf16 v[80:95], v[4:7], v[128:131], v[80:95]
	ds_read_b128 v[4:7], v13 offset:18432
	s_waitcnt lgkmcnt(0)
	v_mfma_f32_32x32x16_bf16 v[96:111], v[4:7], v[112:115], v[96:111]
	v_mfma_f32_32x32x16_bf16 v[80:95], v[4:7], v[116:119], v[80:95]
	s_nop 10
	v_max_f32_e32 v4, v97, v97
	v_max_f32_e32 v5, v96, v96
	v_max_f32_e32 v4, v5, v4
	v_max3_f32 v4, v4, v98, v99
	v_max3_f32 v4, v4, v100, v101
	v_max3_f32 v4, v4, v102, v103
	v_max3_f32 v4, v4, v104, v105
	v_max3_f32 v4, v4, v106, v107
	v_max3_f32 v4, v4, v108, v109
	v_max3_f32 v4, v4, v110, v111
	ds_bpermute_b32 v5, v0, v4
	s_waitcnt lgkmcnt(0)
	v_max_f32_e32 v5, v5, v5
	v_max_f32_e32 v4, v4, v5
	v_add_f32_e32 v5, 0x41000000, v1
	v_cmp_gt_f32_e32 vcc, v4, v5
	s_cbranch_vccz .LBB0_220
	v_max_f32_e32 v4, v4, v4
	v_max_f32_e32 v5, v1, v1
	v_max_f32_e32 v5, v5, v4
	v_sub_f32_e32 v1, v1, v5
	v_exp_f32_e32 v4, v1
	v_mov_b32_e32 v1, v5
	v_mul_f32_e32 v12, v12, v4
	v_pk_mul_f32 v[78:79], v[78:79], v[4:5] op_sel_hi:[1,0]
	v_pk_mul_f32 v[76:77], v[76:77], v[4:5] op_sel_hi:[1,0]
	v_pk_mul_f32 v[74:75], v[74:75], v[4:5] op_sel_hi:[1,0]
	v_pk_mul_f32 v[72:73], v[72:73], v[4:5] op_sel_hi:[1,0]
	v_pk_mul_f32 v[70:71], v[70:71], v[4:5] op_sel_hi:[1,0]
	v_pk_mul_f32 v[68:69], v[68:69], v[4:5] op_sel_hi:[1,0]
	v_pk_mul_f32 v[66:67], v[66:67], v[4:5] op_sel_hi:[1,0]
	v_pk_mul_f32 v[64:65], v[64:65], v[4:5] op_sel_hi:[1,0]
	v_pk_mul_f32 v[62:63], v[62:63], v[4:5] op_sel_hi:[1,0]
	v_pk_mul_f32 v[60:61], v[60:61], v[4:5] op_sel_hi:[1,0]
	v_pk_mul_f32 v[58:59], v[58:59], v[4:5] op_sel_hi:[1,0]
	v_pk_mul_f32 v[56:57], v[56:57], v[4:5] op_sel_hi:[1,0]
	v_pk_mul_f32 v[54:55], v[54:55], v[4:5] op_sel_hi:[1,0]
	v_pk_mul_f32 v[52:53], v[52:53], v[4:5] op_sel_hi:[1,0]
	v_pk_mul_f32 v[50:51], v[50:51], v[4:5] op_sel_hi:[1,0]
	v_pk_mul_f32 v[48:49], v[48:49], v[4:5] op_sel_hi:[1,0]

.LBB0_271:
	v_sub_f32_e32 v4, v96, v1
	v_exp_f32_e32 v9, v4
	v_sub_f32_e32 v5, v97, v1
	v_exp_f32_e32 v10, v5
	v_sub_f32_e32 v5, v98, v1
	v_exp_f32_e32 v11, v5
	v_sub_f32_e32 v5, v99, v1
	v_exp_f32_e32 v13, v5
	v_sub_f32_e32 v5, v100, v1
	v_add_f32_e32 v4, 0, v9
	v_exp_f32_e32 v14, v5
	v_sub_f32_e32 v5, v101, v1
	v_add_f32_e32 v4, v10, v4
	v_exp_f32_e32 v15, v5
	v_sub_f32_e32 v5, v102, v1
	v_add_f32_e32 v4, v11, v4
	v_exp_f32_e32 v96, v5
	v_sub_f32_e32 v5, v103, v1
	v_add_f32_e32 v4, v13, v4
	v_exp_f32_e32 v97, v5
	v_sub_f32_e32 v5, v104, v1
	v_add_f32_e32 v4, v14, v4
	v_exp_f32_e32 v5, v5
	v_sub_f32_e32 v6, v105, v1
	v_add_f32_e32 v4, v15, v4
	v_exp_f32_e32 v6, v6
	v_sub_f32_e32 v7, v106, v1
	v_add_f32_e32 v4, v96, v4
	v_exp_f32_e32 v7, v7
	v_sub_f32_e32 v12, v107, v1
	v_add_f32_e32 v4, v97, v4
	v_exp_f32_e32 v12, v12
	v_sub_f32_e32 v98, v108, v1
	v_add_f32_e32 v4, v5, v4
	v_exp_f32_e32 v98, v98
	v_sub_f32_e32 v99, v109, v1
	v_add_f32_e32 v4, v6, v4
	v_exp_f32_e32 v99, v99
	v_sub_f32_e32 v100, v110, v1
	v_add_f32_e32 v4, v7, v4
	v_exp_f32_e32 v100, v100
	v_sub_f32_e32 v101, v111, v1
	v_add_f32_e32 v4, v12, v4
	v_exp_f32_e32 v101, v101
	v_add_f32_e32 v4, v98, v4
	v_add_f32_e32 v4, v99, v4
	v_add_f32_e32 v4, v100, v4
	v_add_f32_e32 v4, v101, v4
	v_add_f32_e32 v3, v3, v4
	v_cvt_pk_bf16_f32 v4, v5, v6
	v_cvt_pk_bf16_f32 v5, v7, v12
	v_cvt_pk_bf16_f32 v12, v9, v10
	v_sub_f32_e32 v9, v80, v205
	v_cvt_pk_bf16_f32 v13, v11, v13
	v_exp_f32_e32 v9, v9
	v_sub_f32_e32 v11, v81, v205
	v_exp_f32_e32 v11, v11
	v_sub_f32_e32 v80, v82, v205
	v_exp_f32_e32 v81, v80
	v_sub_f32_e32 v80, v83, v205
	v_exp_f32_e32 v82, v80
	v_sub_f32_e32 v80, v84, v205
	v_add_f32_e32 v10, 0, v9
	v_exp_f32_e32 v83, v80
	v_sub_f32_e32 v80, v85, v205
	v_add_f32_e32 v10, v11, v10
	v_exp_f32_e32 v84, v80
	v_sub_f32_e32 v80, v86, v205
	v_add_f32_e32 v10, v81, v10
	v_exp_f32_e32 v85, v80
	v_sub_f32_e32 v80, v87, v205
	v_add_f32_e32 v10, v82, v10
	v_exp_f32_e32 v86, v80
	v_sub_f32_e32 v80, v88, v205
	v_add_f32_e32 v10, v83, v10
	v_exp_f32_e32 v87, v80
	v_sub_f32_e32 v80, v89, v205
	v_add_f32_e32 v10, v84, v10
	v_exp_f32_e32 v88, v80
	v_sub_f32_e32 v80, v90, v205
	v_add_f32_e32 v10, v85, v10
	v_exp_f32_e32 v89, v80
	v_sub_f32_e32 v80, v91, v205
	v_add_f32_e32 v10, v86, v10
	v_exp_f32_e32 v90, v80
	v_sub_f32_e32 v80, v92, v205
	v_add_f32_e32 v10, v87, v10
	v_exp_f32_e32 v91, v80
	v_sub_f32_e32 v80, v93, v205
	v_add_f32_e32 v10, v88, v10
	v_exp_f32_e32 v92, v80
	v_sub_f32_e32 v80, v94, v205
	v_add_f32_e32 v10, v89, v10
	v_exp_f32_e32 v93, v80
	v_sub_f32_e32 v80, v95, v205
	v_add_f32_e32 v10, v90, v10
	v_exp_f32_e32 v94, v80
	v_add_f32_e32 v10, v91, v10
	v_add_f32_e32 v10, v92, v10
	v_add_f32_e32 v10, v93, v10
	v_add_f32_e32 v10, v94, v10
	v_add_f32_e32 v208, v8, v10
	v_cvt_pk_bf16_f32 v81, v81, v82
	v_cvt_pk_bf16_f32 v82, v83, v84
	v_cvt_pk_bf16_f32 v8, v87, v88
	v_lshl_add_u32 v84, v204, 1, v219
	v_lshl_add_u32 v88, v203, 1, v219
	v_cvt_pk_bf16_f32 v80, v9, v11
	v_cvt_pk_bf16_f32 v83, v85, v86
	v_cvt_pk_bf16_f32 v9, v89, v90
	v_cvt_pk_bf16_f32 v10, v91, v92
	ds_read_b64 v[238:239], v84 offset:8192
	ds_read_b64 v[242:243], v84 offset:12288
	ds_read_b64 v[240:241], v88 offset:8192
	ds_read_b64 v[244:245], v88 offset:12288
	v_cvt_pk_bf16_f32 v11, v93, v94
	v_cvt_pk_bf16_f32 v14, v14, v15
	v_cvt_pk_bf16_f32 v15, v96, v97
	s_waitcnt lgkmcnt(0)
	v_mfma_f32_32x32x16_bf16 v[64:79], v[238:241], v[12:15], v[64:79]
	v_cvt_pk_bf16_f32 v6, v98, v99
	v_cvt_pk_bf16_f32 v7, v100, v101
	s_add_i32 s39, s39, 1
	s_add_i32 s2, s40, 1
	s_cmp_lg_u32 s40, 2
	s_cselect_b32 s40, s2, 0
	s_mov_b64 s[2:3], 0x1000
	v_mfma_f32_32x32x16_bf16 v[32:47], v[238:241], v[80:83], v[32:47]
	v_lshl_add_u64 v[162:163], v[162:163], 0, s[22:23]
	v_lshl_add_u64 v[164:165], v[164:165], 0, s[2:3]
	v_lshl_add_u64 v[166:167], v[166:167], 0, s[24:25]
	s_cmp_lg_u32 s39, 39
	v_mfma_f32_32x32x16_bf16 v[48:63], v[242:245], v[12:15], v[48:63]
	v_lshl_add_u32 v12, v202, 1, v219
	ds_read2st64_b64 v[12:15], v12 offset0:16 offset1:24
	s_waitcnt lgkmcnt(0)
	v_mov_b32_e32 v84, v12
	v_mfma_f32_32x32x16_bf16 v[16:31], v[242:245], v[80:83], v[16:31]
	v_lshl_add_u32 v80, v201, 1, v219
	ds_read2st64_b64 v[80:83], v80 offset0:16 offset1:24
	v_mov_b32_e32 v85, v13
	s_waitcnt lgkmcnt(0)
	v_mov_b32_e32 v86, v80
	v_mov_b32_e32 v87, v81
	v_mov_b32_e32 v80, v14
	v_mov_b32_e32 v81, v15
	v_mfma_f32_32x32x16_bf16 v[64:79], v[84:87], v[4:7], v[64:79]
	v_mfma_f32_32x32x16_bf16 v[32:47], v[84:87], v[8:11], v[32:47]
	v_mfma_f32_32x32x16_bf16 v[48:63], v[80:83], v[4:7], v[48:63]
	v_mfma_f32_32x32x16_bf16 v[16:31], v[80:83], v[8:11], v[16:31]
	s_cbranch_scc0 .LBB0_282

.LBB0_294:
	v_sub_f32_e32 v4, v96, v1
	v_exp_f32_e32 v9, v4
	v_sub_f32_e32 v5, v97, v1
	v_exp_f32_e32 v10, v5
	v_sub_f32_e32 v5, v98, v1
	v_exp_f32_e32 v11, v5
	v_sub_f32_e32 v5, v99, v1
	v_exp_f32_e32 v13, v5
	v_sub_f32_e32 v5, v100, v1
	v_add_f32_e32 v4, 0, v9
	v_exp_f32_e32 v14, v5
	v_sub_f32_e32 v5, v101, v1
	v_add_f32_e32 v4, v10, v4
	v_exp_f32_e32 v15, v5
	v_sub_f32_e32 v5, v102, v1
	v_add_f32_e32 v4, v11, v4
	v_exp_f32_e32 v96, v5
	v_sub_f32_e32 v5, v103, v1
	v_add_f32_e32 v4, v13, v4
	v_exp_f32_e32 v97, v5
	v_sub_f32_e32 v5, v104, v1
	v_add_f32_e32 v4, v14, v4
	v_exp_f32_e32 v5, v5
	v_sub_f32_e32 v6, v105, v1
	v_add_f32_e32 v4, v15, v4
	v_exp_f32_e32 v6, v6
	v_sub_f32_e32 v7, v106, v1
	v_add_f32_e32 v4, v96, v4
	v_exp_f32_e32 v7, v7
	v_sub_f32_e32 v12, v107, v1
	v_add_f32_e32 v4, v97, v4
	v_exp_f32_e32 v12, v12
	v_sub_f32_e32 v98, v108, v1
	v_add_f32_e32 v4, v5, v4
	v_exp_f32_e32 v98, v98
	v_sub_f32_e32 v99, v109, v1
	v_add_f32_e32 v4, v6, v4
	v_exp_f32_e32 v99, v99
	v_sub_f32_e32 v100, v110, v1
	v_add_f32_e32 v4, v7, v4
	v_exp_f32_e32 v100, v100
	v_sub_f32_e32 v101, v111, v1
	v_add_f32_e32 v4, v12, v4
	v_exp_f32_e32 v101, v101
	v_add_f32_e32 v4, v98, v4
	v_add_f32_e32 v4, v99, v4
	v_add_f32_e32 v4, v100, v4
	v_add_f32_e32 v4, v101, v4
	v_add_f32_e32 v3, v3, v4
	v_cvt_pk_bf16_f32 v4, v5, v6
	v_cvt_pk_bf16_f32 v5, v7, v12
	v_cvt_pk_bf16_f32 v12, v9, v10
	v_sub_f32_e32 v9, v80, v159
	v_cvt_pk_bf16_f32 v13, v11, v13
	v_exp_f32_e32 v9, v9
	v_sub_f32_e32 v11, v81, v159
	v_exp_f32_e32 v11, v11
	v_sub_f32_e32 v80, v82, v159
	v_exp_f32_e32 v81, v80
	v_sub_f32_e32 v80, v83, v159
	v_exp_f32_e32 v82, v80
	v_sub_f32_e32 v80, v84, v159
	v_add_f32_e32 v10, 0, v9
	v_exp_f32_e32 v83, v80
	v_sub_f32_e32 v80, v85, v159
	v_add_f32_e32 v10, v11, v10
	v_exp_f32_e32 v84, v80
	v_sub_f32_e32 v80, v86, v159
	v_add_f32_e32 v10, v81, v10
	v_exp_f32_e32 v85, v80
	v_sub_f32_e32 v80, v87, v159
	v_add_f32_e32 v10, v82, v10
	v_exp_f32_e32 v86, v80
	v_sub_f32_e32 v80, v88, v159
	v_add_f32_e32 v10, v83, v10
	v_exp_f32_e32 v87, v80
	v_sub_f32_e32 v80, v89, v159
	v_add_f32_e32 v10, v84, v10
	v_exp_f32_e32 v88, v80
	v_sub_f32_e32 v80, v90, v159
	v_add_f32_e32 v10, v85, v10
	v_exp_f32_e32 v89, v80
	v_sub_f32_e32 v80, v91, v159
	v_add_f32_e32 v10, v86, v10
	v_exp_f32_e32 v90, v80
	v_sub_f32_e32 v80, v92, v159
	v_add_f32_e32 v10, v87, v10
	v_exp_f32_e32 v91, v80
	v_sub_f32_e32 v80, v93, v159
	v_add_f32_e32 v10, v88, v10
	v_exp_f32_e32 v92, v80
	v_sub_f32_e32 v80, v94, v159
	v_add_f32_e32 v10, v89, v10
	v_exp_f32_e32 v93, v80
	v_sub_f32_e32 v80, v95, v159
	v_add_f32_e32 v10, v90, v10
	v_exp_f32_e32 v94, v80
	v_add_f32_e32 v10, v91, v10
	v_add_f32_e32 v10, v92, v10
	v_add_f32_e32 v10, v93, v10
	v_add_f32_e32 v10, v94, v10
	v_add_f32_e32 v162, v8, v10
	v_cvt_pk_bf16_f32 v81, v81, v82
	v_cvt_pk_bf16_f32 v82, v83, v84
	v_cvt_pk_bf16_f32 v8, v87, v88
	v_lshl_add_u32 v84, v158, 1, v204
	v_lshl_add_u32 v88, v157, 1, v204
	v_cvt_pk_bf16_f32 v80, v9, v11
	v_cvt_pk_bf16_f32 v83, v85, v86
	v_cvt_pk_bf16_f32 v9, v89, v90
	v_cvt_pk_bf16_f32 v10, v91, v92
	ds_read_b64 v[222:223], v84 offset:8192
	ds_read_b64 v[226:227], v84 offset:12288
	ds_read_b64 v[224:225], v88 offset:8192
	ds_read_b64 v[228:229], v88 offset:12288
	v_cvt_pk_bf16_f32 v11, v93, v94
	v_cvt_pk_bf16_f32 v14, v14, v15
	v_cvt_pk_bf16_f32 v15, v96, v97
	s_waitcnt lgkmcnt(0)
	v_mfma_f32_32x32x16_bf16 v[64:79], v[222:225], v[12:15], v[64:79]
	v_cvt_pk_bf16_f32 v6, v98, v99
	v_cvt_pk_bf16_f32 v7, v100, v101
	s_add_i32 s40, s40, 1
	s_add_i32 s2, s41, 1
	s_cmp_lg_u32 s41, 2
	s_cselect_b32 s41, s2, 0
	s_mov_b64 s[2:3], 0x2000
	v_mfma_f32_32x32x16_bf16 v[32:47], v[222:225], v[80:83], v[32:47]
	v_lshl_add_u64 v[150:151], v[150:151], 0, s[22:23]
	v_lshl_add_u64 v[152:153], v[152:153], 0, s[2:3]
	s_cmp_lg_u32 s40, 39
	v_mfma_f32_32x32x16_bf16 v[48:63], v[226:229], v[12:15], v[48:63]
	v_lshl_add_u32 v12, v156, 1, v204
	ds_read2st64_b64 v[12:15], v12 offset0:16 offset1:24
	s_waitcnt lgkmcnt(0)
	v_mov_b32_e32 v84, v12
	v_mfma_f32_32x32x16_bf16 v[16:31], v[226:229], v[80:83], v[16:31]
	v_lshl_add_u32 v80, v155, 1, v204
	ds_read2st64_b64 v[80:83], v80 offset0:16 offset1:24
	v_mov_b32_e32 v85, v13
	s_waitcnt lgkmcnt(0)
	v_mov_b32_e32 v86, v80
	v_mov_b32_e32 v87, v81
	v_mov_b32_e32 v80, v14
	v_mov_b32_e32 v81, v15
	v_mfma_f32_32x32x16_bf16 v[64:79], v[84:87], v[4:7], v[64:79]
	v_mfma_f32_32x32x16_bf16 v[32:47], v[84:87], v[8:11], v[32:47]
	v_mfma_f32_32x32x16_bf16 v[48:63], v[80:83], v[4:7], v[48:63]
	v_mfma_f32_32x32x16_bf16 v[16:31], v[80:83], v[8:11], v[16:31]
	s_cbranch_scc0 .LBB0_305
